# FFN-out GEMM k-loop software-pipelined by hand (next tile's LDS fragments read and tile t+3's LDS-DMA issued under the current tile's MFMAs)
# speedup vs baseline: 1.0523x; 1.0006x over previous
.LBB0_52:
	s_ashr_i32 s0, s5, 31
	s_lshr_b32 s0, s0, 27
	s_add_i32 s0, s5, s0
	s_and_b32 s1, s0, 0xffffffe0
	s_sub_i32 s7, s5, s1
	s_lshl_b32 s0, s0, 2
	s_and_b32 s6, s0, 0xffffff80
	s_mul_i32 s0, s7, 0x84000
	s_ashr_i32 s1, s0, 31
	s_lshl_b64 s[0:1], s[0:1], 1
	v_lshl_add_u64 v[0:1], v[98:99], 0, s[0:1]
	v_readfirstlane_b32 s8, v142
	v_lshl_add_u64 v[4:5], v[0:1], 0, v[112:113]
	s_mov_b32 m0, s8
	v_readfirstlane_b32 s8, v143
	global_load_lds_dwordx4 v[4:5], off
	v_lshl_add_u64 v[6:7], v[0:1], 0, v[114:115]
	s_mov_b32 m0, s8
	v_readfirstlane_b32 s8, v144
	v_add_u32_e32 v10, 0x3000, v142
	v_mad_i64_i32 v[2:3], s[10:11], s6, v188, v[100:101]
	global_load_lds_dwordx4 v[6:7], off
	v_lshl_add_u64 v[0:1], v[0:1], 0, v[96:97]
	s_mov_b32 m0, s8
	v_readfirstlane_b32 s8, v10
	v_add_u32_e32 v10, 0x4000, v142
	global_load_lds_dwordx4 v[0:1], off
	v_lshl_add_u64 v[8:9], v[2:3], 0, v[112:113]
	s_mov_b32 m0, s8
	v_readfirstlane_b32 s8, v10
	v_add_u32_e32 v10, 0x5000, v142
	global_load_lds_dwordx4 v[8:9], off
	v_lshl_add_u64 v[2:3], v[2:3], 0, v[114:115]
	s_mov_b32 m0, s8
	v_readfirstlane_b32 s8, v10
	global_load_lds_dwordx4 v[2:3], off
	v_lshl_add_u64 v[4:5], v[4:5], 0, 64
	s_mov_b32 m0, s8
	v_lshl_add_u64 v[0:1], v[0:1], 0, 64
	global_load_lds_dwordx4 v[4:5], off
	v_lshl_add_u64 v[4:5], v[6:7], 0, 64
	v_add_u32_e32 v6, 0x6000, v142
	s_mov_b32 s9, 2
	v_readfirstlane_b32 s8, v6
	s_mov_b32 m0, s8
	v_mad_i64_i32 v[116:117], s[10:11], s6, v188, v[102:103]
	global_load_lds_dwordx4 v[4:5], off
	v_add_u32_e32 v4, 0x7000, v142
	v_mad_i64_i32 v[118:119], s[10:11], s6, v188, v[104:105]
	v_readfirstlane_b32 s8, v4
	v_add_u32_e32 v4, 0x8000, v142
	s_mov_b32 m0, s8
	v_readfirstlane_b32 s8, v4
	global_load_lds_dwordx4 v[0:1], off
	v_lshl_add_u64 v[0:1], v[8:9], 0, 64
	s_mov_b32 m0, s8
	v_lshl_add_u64 v[120:121], v[106:107], 0, s[0:1]
	global_load_lds_dwordx4 v[0:1], off
	v_lshl_add_u64 v[0:1], v[2:3], 0, 64
	v_add_u32_e32 v2, 0x9000, v142
	v_lshl_add_u64 v[122:123], v[108:109], 0, s[0:1]
	v_readfirstlane_b32 s8, v2
	s_mov_b32 m0, s8
	v_lshl_add_u64 v[124:125], v[110:111], 0, s[0:1]
	global_load_lds_dwordx4 v[0:1], off
	v_mov_b32_e32 v0, 0
	s_mov_b32 s8, 0
	s_mov_b64 s[0:1], 0
	v_mov_b32_e32 v1, v0
	v_mov_b32_e32 v2, v0
	v_mov_b32_e32 v3, v0
	v_mov_b32_e32 v12, v0
	v_mov_b32_e32 v13, v0
	v_mov_b32_e32 v14, v0
	v_mov_b32_e32 v15, v0
	v_mov_b32_e32 v4, v0
	v_mov_b32_e32 v5, v0
	v_mov_b32_e32 v6, v0
	v_mov_b32_e32 v7, v0
	v_mov_b32_e32 v8, v0
	v_mov_b32_e32 v9, v0
	v_mov_b32_e32 v10, v0
	v_mov_b32_e32 v11, v0
	v_mov_b32_e32 v16, v0
	v_mov_b32_e32 v17, v0
	v_mov_b32_e32 v18, v0
	v_mov_b32_e32 v19, v0
	v_mov_b32_e32 v20, v0
	v_mov_b32_e32 v21, v0
	v_mov_b32_e32 v22, v0
	v_mov_b32_e32 v23, v0
	v_mov_b32_e32 v24, v0
	v_mov_b32_e32 v25, v0
	v_mov_b32_e32 v26, v0
	v_mov_b32_e32 v27, v0
	v_mov_b32_e32 v28, v0
	v_mov_b32_e32 v29, v0
	v_mov_b32_e32 v30, v0
	v_mov_b32_e32 v31, v0
	v_mov_b32_e32 v32, v0
	v_mov_b32_e32 v33, v0
	v_mov_b32_e32 v34, v0
	v_mov_b32_e32 v35, v0
	v_mov_b32_e32 v36, v0
	v_mov_b32_e32 v37, v0
	v_mov_b32_e32 v38, v0
	v_mov_b32_e32 v39, v0
	v_mov_b32_e32 v40, v0
	v_mov_b32_e32 v41, v0
	v_mov_b32_e32 v42, v0
	v_mov_b32_e32 v43, v0
	v_mov_b32_e32 v44, v0
	v_mov_b32_e32 v45, v0
	v_mov_b32_e32 v46, v0
	v_mov_b32_e32 v47, v0
	v_mov_b32_e32 v48, v0
	v_mov_b32_e32 v49, v0
	v_mov_b32_e32 v50, v0
	v_mov_b32_e32 v51, v0
	v_mov_b32_e32 v52, v0
	v_mov_b32_e32 v53, v0
	v_mov_b32_e32 v54, v0
	v_mov_b32_e32 v55, v0
	v_mov_b32_e32 v56, v0
	v_mov_b32_e32 v57, v0
	v_mov_b32_e32 v58, v0
	v_mov_b32_e32 v59, v0
	v_mov_b32_e32 v60, v0
	v_mov_b32_e32 v61, v0
	v_mov_b32_e32 v62, v0
	v_mov_b32_e32 v63, v0
	v_mov_b32_e32 v64, v0
	v_mov_b32_e32 v65, v0
	v_mov_b32_e32 v66, v0
	v_mov_b32_e32 v67, v0
	v_mov_b32_e32 v68, v0
	v_mov_b32_e32 v69, v0
	v_mov_b32_e32 v70, v0
	v_mov_b32_e32 v71, v0
	v_mov_b32_e32 v72, v0
	v_mov_b32_e32 v73, v0
	v_mov_b32_e32 v74, v0
	v_mov_b32_e32 v75, v0
	v_mov_b32_e32 v76, v0
	v_mov_b32_e32 v77, v0
	v_mov_b32_e32 v78, v0
	v_mov_b32_e32 v79, v0
	v_mov_b32_e32 v80, v0
	v_mov_b32_e32 v81, v0
	v_mov_b32_e32 v82, v0
	v_mov_b32_e32 v83, v0
	v_mov_b32_e32 v84, v0
	v_mov_b32_e32 v85, v0
	v_mov_b32_e32 v86, v0
	v_mov_b32_e32 v87, v0
	v_mov_b32_e32 v88, v0
	v_mov_b32_e32 v89, v0
	v_mov_b32_e32 v90, v0
	v_mov_b32_e32 v91, v0
	v_mov_b32_e32 v92, v0
	v_mov_b32_e32 v93, v0
	v_mov_b32_e32 v94, v0
	v_mov_b32_e32 v95, v0
	v_readfirstlane_b32 s34, v142
	s_mov_b32 s36, 0x5000
	s_mov_b32 s37, 0xffff6000
	s_add_u32 s39, s34, 0xa000
	v_lshl_add_u64 v[126:127], v[124:125], 0, s[2:3]
	s_mov_b32 m0, s39
	s_nop 0
	global_load_lds_dwordx4 v[126:127], off
	v_lshl_add_u64 v[126:127], v[122:123], 0, s[2:3]
	s_add_u32 m0, s39, 0x1000
	s_nop 0
	global_load_lds_dwordx4 v[126:127], off
	v_lshl_add_u64 v[126:127], v[120:121], 0, s[2:3]
	s_add_u32 m0, s39, 0x2000
	s_nop 0
	global_load_lds_dwordx4 v[126:127], off
	v_lshl_add_u64 v[126:127], v[118:119], 0, s[2:3]
	s_add_u32 m0, s39, 0x3000
	s_nop 0
	global_load_lds_dwordx4 v[126:127], off
	v_lshl_add_u64 v[126:127], v[116:117], 0, s[2:3]
	s_add_u32 m0, s39, 0x4000
	s_nop 0
	global_load_lds_dwordx4 v[126:127], off
	v_lshl_add_u64 v[124:125], v[124:125], 0, s[30:31]
	v_lshl_add_u64 v[122:123], v[122:123], 0, s[30:31]
	v_lshl_add_u64 v[120:121], v[120:121], 0, s[30:31]
	v_lshl_add_u64 v[236:237], v[118:119], 0, s[30:31]
	v_lshl_add_u64 v[126:127], v[116:117], 0, s[30:31]
	v_add_u32_e32 v170, v147, v128
	v_add_u32_e32 v172, v149, v148
	s_mov_b32 s35, 0
	s_mov_b32 s41, 42
	s_waitcnt vmcnt(10)
	s_barrier
	ds_read_b128 v[134:137], v170
	ds_read_b128 v[138:141], v170 offset:1024
	ds_read_b128 v[150:153], v170 offset:2048
	ds_read_b128 v[154:157], v170 offset:3072
	ds_read_b128 v[158:161], v170 offset:4096
	ds_read_b128 v[162:165], v170 offset:5120
	ds_read_b128 v[166:169], v172 offset:12288
	ds_read_b128 v[200:203], v172 offset:13312
	ds_read_b128 v[204:207], v172 offset:14336
	ds_read_b128 v[208:211], v172 offset:15360
.Lk_ffo:
	s_waitcnt lgkmcnt(0)
	v_mfma_f32_16x16x32_bf16 v[92:95], v[166:169], v[134:137], v[92:95]
	s_waitcnt vmcnt(5)
	s_barrier
	v_mfma_f32_16x16x32_bf16 v[88:91], v[200:203], v[134:137], v[88:91]
	s_cmp_eq_u32 s35, 0xa000
	s_cselect_b32 s38, s37, s36
	s_add_u32 s39, s34, s35
	v_mfma_f32_16x16x32_bf16 v[84:87], v[204:207], v[134:137], v[84:87]
	v_add_u32_e32 v170, s38, v170
	v_add_u32_e32 v172, s38, v172
	s_add_u32 s35, s35, s38
	v_mfma_f32_16x16x32_bf16 v[80:83], v[208:211], v[134:137], v[80:83]
	ds_read_b128 v[212:215], v170
	v_mfma_f32_16x16x32_bf16 v[76:79], v[166:169], v[138:141], v[76:79]
	ds_read_b128 v[216:219], v170 offset:1024
	v_mfma_f32_16x16x32_bf16 v[72:75], v[200:203], v[138:141], v[72:75]
	ds_read_b128 v[220:223], v170 offset:2048
	v_mfma_f32_16x16x32_bf16 v[68:71], v[204:207], v[138:141], v[68:71]
	ds_read_b128 v[224:227], v170 offset:3072
	v_mfma_f32_16x16x32_bf16 v[64:67], v[208:211], v[138:141], v[64:67]
	ds_read_b128 v[228:231], v170 offset:4096
	v_mfma_f32_16x16x32_bf16 v[60:63], v[166:169], v[150:153], v[60:63]
	ds_read_b128 v[232:235], v170 offset:5120
	v_mfma_f32_16x16x32_bf16 v[56:59], v[200:203], v[150:153], v[56:59]
	ds_read_b128 v[244:247], v172 offset:12288
	v_mfma_f32_16x16x32_bf16 v[52:55], v[204:207], v[150:153], v[52:55]
	ds_read_b128 v[248:251], v172 offset:13312
	v_mfma_f32_16x16x32_bf16 v[48:51], v[208:211], v[150:153], v[48:51]
	ds_read_b128 v[252:255], v172 offset:14336
	v_mfma_f32_16x16x32_bf16 v[44:47], v[166:169], v[154:157], v[44:47]
	ds_read_b128 v[116:119], v172 offset:15360
	v_mfma_f32_16x16x32_bf16 v[40:43], v[200:203], v[154:157], v[40:43]
	s_mov_b32 m0, s39
	v_mfma_f32_16x16x32_bf16 v[36:39], v[204:207], v[154:157], v[36:39]
	global_load_lds_dwordx4 v[124:125], off
	v_lshl_add_u64 v[124:125], v[124:125], 0, 64
	v_mfma_f32_16x16x32_bf16 v[32:35], v[208:211], v[154:157], v[32:35]
	s_add_u32 m0, s39, 0x1000
	v_mfma_f32_16x16x32_bf16 v[28:31], v[166:169], v[158:161], v[28:31]
	global_load_lds_dwordx4 v[122:123], off
	v_lshl_add_u64 v[122:123], v[122:123], 0, 64
	v_mfma_f32_16x16x32_bf16 v[24:27], v[200:203], v[158:161], v[24:27]
	s_add_u32 m0, s39, 0x2000
	v_mfma_f32_16x16x32_bf16 v[20:23], v[204:207], v[158:161], v[20:23]
	global_load_lds_dwordx4 v[120:121], off
	v_lshl_add_u64 v[120:121], v[120:121], 0, 64
	v_mfma_f32_16x16x32_bf16 v[16:19], v[208:211], v[158:161], v[16:19]
	s_add_u32 m0, s39, 0x3000
	v_mfma_f32_16x16x32_bf16 v[8:11], v[166:169], v[162:165], v[8:11]
	global_load_lds_dwordx4 v[236:237], off
	v_lshl_add_u64 v[236:237], v[236:237], 0, 64
	v_mfma_f32_16x16x32_bf16 v[4:7], v[200:203], v[162:165], v[4:7]
	s_add_u32 m0, s39, 0x4000
	v_mfma_f32_16x16x32_bf16 v[12:15], v[204:207], v[162:165], v[12:15]
	global_load_lds_dwordx4 v[126:127], off
	v_lshl_add_u64 v[126:127], v[126:127], 0, 64
	v_mfma_f32_16x16x32_bf16 v[0:3], v[208:211], v[162:165], v[0:3]
	s_waitcnt lgkmcnt(0)
	v_mfma_f32_16x16x32_bf16 v[92:95], v[244:247], v[212:215], v[92:95]
	s_waitcnt vmcnt(5)
	s_barrier
	v_mfma_f32_16x16x32_bf16 v[88:91], v[248:251], v[212:215], v[88:91]
	s_cmp_eq_u32 s35, 0xa000
	s_cselect_b32 s38, s37, s36
	s_add_u32 s39, s34, s35
	v_mfma_f32_16x16x32_bf16 v[84:87], v[252:255], v[212:215], v[84:87]
	v_add_u32_e32 v170, s38, v170
	v_add_u32_e32 v172, s38, v172
	s_add_u32 s35, s35, s38
	v_mfma_f32_16x16x32_bf16 v[80:83], v[116:119], v[212:215], v[80:83]
	ds_read_b128 v[134:137], v170
	v_mfma_f32_16x16x32_bf16 v[76:79], v[244:247], v[216:219], v[76:79]
	ds_read_b128 v[138:141], v170 offset:1024
	v_mfma_f32_16x16x32_bf16 v[72:75], v[248:251], v[216:219], v[72:75]
	ds_read_b128 v[150:153], v170 offset:2048
	v_mfma_f32_16x16x32_bf16 v[68:71], v[252:255], v[216:219], v[68:71]
	ds_read_b128 v[154:157], v170 offset:3072
	v_mfma_f32_16x16x32_bf16 v[64:67], v[116:119], v[216:219], v[64:67]
	ds_read_b128 v[158:161], v170 offset:4096
	v_mfma_f32_16x16x32_bf16 v[60:63], v[244:247], v[220:223], v[60:63]
	ds_read_b128 v[162:165], v170 offset:5120
	v_mfma_f32_16x16x32_bf16 v[56:59], v[248:251], v[220:223], v[56:59]
	ds_read_b128 v[166:169], v172 offset:12288
	v_mfma_f32_16x16x32_bf16 v[52:55], v[252:255], v[220:223], v[52:55]
	ds_read_b128 v[200:203], v172 offset:13312
	v_mfma_f32_16x16x32_bf16 v[48:51], v[116:119], v[220:223], v[48:51]
	ds_read_b128 v[204:207], v172 offset:14336
	v_mfma_f32_16x16x32_bf16 v[44:47], v[244:247], v[224:227], v[44:47]
	ds_read_b128 v[208:211], v172 offset:15360
	v_mfma_f32_16x16x32_bf16 v[40:43], v[248:251], v[224:227], v[40:43]
	s_mov_b32 m0, s39
	v_mfma_f32_16x16x32_bf16 v[36:39], v[252:255], v[224:227], v[36:39]
	global_load_lds_dwordx4 v[124:125], off
	v_lshl_add_u64 v[124:125], v[124:125], 0, 64
	v_mfma_f32_16x16x32_bf16 v[32:35], v[116:119], v[224:227], v[32:35]
	s_add_u32 m0, s39, 0x1000
	v_mfma_f32_16x16x32_bf16 v[28:31], v[244:247], v[228:231], v[28:31]
	global_load_lds_dwordx4 v[122:123], off
	v_lshl_add_u64 v[122:123], v[122:123], 0, 64
	v_mfma_f32_16x16x32_bf16 v[24:27], v[248:251], v[228:231], v[24:27]
	s_add_u32 m0, s39, 0x2000
	v_mfma_f32_16x16x32_bf16 v[20:23], v[252:255], v[228:231], v[20:23]
	global_load_lds_dwordx4 v[120:121], off
	v_lshl_add_u64 v[120:121], v[120:121], 0, 64
	v_mfma_f32_16x16x32_bf16 v[16:19], v[116:119], v[228:231], v[16:19]
	s_add_u32 m0, s39, 0x3000
	v_mfma_f32_16x16x32_bf16 v[8:11], v[244:247], v[232:235], v[8:11]
	global_load_lds_dwordx4 v[236:237], off
	v_lshl_add_u64 v[236:237], v[236:237], 0, 64
	v_mfma_f32_16x16x32_bf16 v[4:7], v[248:251], v[232:235], v[4:7]
	s_add_u32 m0, s39, 0x4000
	v_mfma_f32_16x16x32_bf16 v[12:15], v[252:255], v[232:235], v[12:15]
	global_load_lds_dwordx4 v[126:127], off
	v_lshl_add_u64 v[126:127], v[126:127], 0, 64
	v_mfma_f32_16x16x32_bf16 v[0:3], v[116:119], v[232:235], v[0:3]
	s_add_i32 s41, s41, -1
	s_cmp_eq_u32 s41, 0
	s_cbranch_scc0 .Lk_ffo
	s_waitcnt lgkmcnt(0)
	v_mfma_f32_16x16x32_bf16 v[92:95], v[166:169], v[134:137], v[92:95]
	s_waitcnt vmcnt(5)
	s_barrier
	v_mfma_f32_16x16x32_bf16 v[88:91], v[200:203], v[134:137], v[88:91]
	s_cmp_eq_u32 s35, 0xa000
	s_cselect_b32 s38, s37, s36
	s_add_u32 s39, s34, s35
	v_mfma_f32_16x16x32_bf16 v[84:87], v[204:207], v[134:137], v[84:87]
	v_add_u32_e32 v170, s38, v170
	v_add_u32_e32 v172, s38, v172
	s_add_u32 s35, s35, s38
	v_mfma_f32_16x16x32_bf16 v[80:83], v[208:211], v[134:137], v[80:83]
	ds_read_b128 v[212:215], v170
	v_mfma_f32_16x16x32_bf16 v[76:79], v[166:169], v[138:141], v[76:79]
	ds_read_b128 v[216:219], v170 offset:1024
	v_mfma_f32_16x16x32_bf16 v[72:75], v[200:203], v[138:141], v[72:75]
	ds_read_b128 v[220:223], v170 offset:2048
	v_mfma_f32_16x16x32_bf16 v[68:71], v[204:207], v[138:141], v[68:71]
	ds_read_b128 v[224:227], v170 offset:3072
	v_mfma_f32_16x16x32_bf16 v[64:67], v[208:211], v[138:141], v[64:67]
	ds_read_b128 v[228:231], v170 offset:4096
	v_mfma_f32_16x16x32_bf16 v[60:63], v[166:169], v[150:153], v[60:63]
	ds_read_b128 v[232:235], v170 offset:5120
	v_mfma_f32_16x16x32_bf16 v[56:59], v[200:203], v[150:153], v[56:59]
	ds_read_b128 v[244:247], v172 offset:12288
	v_mfma_f32_16x16x32_bf16 v[52:55], v[204:207], v[150:153], v[52:55]
	ds_read_b128 v[248:251], v172 offset:13312
	v_mfma_f32_16x16x32_bf16 v[48:51], v[208:211], v[150:153], v[48:51]
	ds_read_b128 v[252:255], v172 offset:14336
	v_mfma_f32_16x16x32_bf16 v[44:47], v[166:169], v[154:157], v[44:47]
	ds_read_b128 v[116:119], v172 offset:15360
	v_mfma_f32_16x16x32_bf16 v[40:43], v[200:203], v[154:157], v[40:43]
	s_mov_b32 m0, s39
	v_mfma_f32_16x16x32_bf16 v[36:39], v[204:207], v[154:157], v[36:39]
	global_load_lds_dwordx4 v[124:125], off
	v_lshl_add_u64 v[124:125], v[124:125], 0, 64
	v_mfma_f32_16x16x32_bf16 v[32:35], v[208:211], v[154:157], v[32:35]
	s_add_u32 m0, s39, 0x1000
	v_mfma_f32_16x16x32_bf16 v[28:31], v[166:169], v[158:161], v[28:31]
	global_load_lds_dwordx4 v[122:123], off
	v_lshl_add_u64 v[122:123], v[122:123], 0, 64
	v_mfma_f32_16x16x32_bf16 v[24:27], v[200:203], v[158:161], v[24:27]
	s_add_u32 m0, s39, 0x2000
	v_mfma_f32_16x16x32_bf16 v[20:23], v[204:207], v[158:161], v[20:23]
	global_load_lds_dwordx4 v[120:121], off
	v_lshl_add_u64 v[120:121], v[120:121], 0, 64
	v_mfma_f32_16x16x32_bf16 v[16:19], v[208:211], v[158:161], v[16:19]
	s_add_u32 m0, s39, 0x3000
	v_mfma_f32_16x16x32_bf16 v[8:11], v[166:169], v[162:165], v[8:11]
	global_load_lds_dwordx4 v[236:237], off
	v_lshl_add_u64 v[236:237], v[236:237], 0, 64
	v_mfma_f32_16x16x32_bf16 v[4:7], v[200:203], v[162:165], v[4:7]
	s_add_u32 m0, s39, 0x4000
	v_mfma_f32_16x16x32_bf16 v[12:15], v[204:207], v[162:165], v[12:15]
	global_load_lds_dwordx4 v[126:127], off
	v_lshl_add_u64 v[126:127], v[126:127], 0, 64
	v_mfma_f32_16x16x32_bf16 v[0:3], v[208:211], v[162:165], v[0:3]
	s_waitcnt lgkmcnt(0)
	v_mfma_f32_16x16x32_bf16 v[92:95], v[244:247], v[212:215], v[92:95]
	s_waitcnt vmcnt(5)
	s_barrier
	v_mfma_f32_16x16x32_bf16 v[88:91], v[248:251], v[212:215], v[88:91]
	s_cmp_eq_u32 s35, 0xa000
	s_cselect_b32 s38, s37, s36
	v_mfma_f32_16x16x32_bf16 v[84:87], v[252:255], v[212:215], v[84:87]
	v_add_u32_e32 v170, s38, v170
	v_add_u32_e32 v172, s38, v172
	s_add_u32 s35, s35, s38
	v_mfma_f32_16x16x32_bf16 v[80:83], v[116:119], v[212:215], v[80:83]
	ds_read_b128 v[134:137], v170
	v_mfma_f32_16x16x32_bf16 v[76:79], v[244:247], v[216:219], v[76:79]
	ds_read_b128 v[138:141], v170 offset:1024
	v_mfma_f32_16x16x32_bf16 v[72:75], v[248:251], v[216:219], v[72:75]
	ds_read_b128 v[150:153], v170 offset:2048
	v_mfma_f32_16x16x32_bf16 v[68:71], v[252:255], v[216:219], v[68:71]
	ds_read_b128 v[154:157], v170 offset:3072
	v_mfma_f32_16x16x32_bf16 v[64:67], v[116:119], v[216:219], v[64:67]
	ds_read_b128 v[158:161], v170 offset:4096
	v_mfma_f32_16x16x32_bf16 v[60:63], v[244:247], v[220:223], v[60:63]
	ds_read_b128 v[162:165], v170 offset:5120
	v_mfma_f32_16x16x32_bf16 v[56:59], v[248:251], v[220:223], v[56:59]
	ds_read_b128 v[166:169], v172 offset:12288
	v_mfma_f32_16x16x32_bf16 v[52:55], v[252:255], v[220:223], v[52:55]
	ds_read_b128 v[200:203], v172 offset:13312
	v_mfma_f32_16x16x32_bf16 v[48:51], v[116:119], v[220:223], v[48:51]
	ds_read_b128 v[204:207], v172 offset:14336
	v_mfma_f32_16x16x32_bf16 v[44:47], v[244:247], v[224:227], v[44:47]
	ds_read_b128 v[208:211], v172 offset:15360
	v_mfma_f32_16x16x32_bf16 v[40:43], v[248:251], v[224:227], v[40:43]
	v_mfma_f32_16x16x32_bf16 v[36:39], v[252:255], v[224:227], v[36:39]
	v_mfma_f32_16x16x32_bf16 v[32:35], v[116:119], v[224:227], v[32:35]
	v_mfma_f32_16x16x32_bf16 v[28:31], v[244:247], v[228:231], v[28:31]
	v_mfma_f32_16x16x32_bf16 v[24:27], v[248:251], v[228:231], v[24:27]
	v_mfma_f32_16x16x32_bf16 v[20:23], v[252:255], v[228:231], v[20:23]
	v_mfma_f32_16x16x32_bf16 v[16:19], v[116:119], v[228:231], v[16:19]
	v_mfma_f32_16x16x32_bf16 v[8:11], v[244:247], v[232:235], v[8:11]
	v_mfma_f32_16x16x32_bf16 v[4:7], v[248:251], v[232:235], v[4:7]
	v_mfma_f32_16x16x32_bf16 v[12:15], v[252:255], v[232:235], v[12:15]
	v_mfma_f32_16x16x32_bf16 v[0:3], v[116:119], v[232:235], v[0:3]
	s_waitcnt lgkmcnt(0)
	v_mfma_f32_16x16x32_bf16 v[92:95], v[166:169], v[134:137], v[92:95]
	s_waitcnt vmcnt(0)
	s_barrier
	v_mfma_f32_16x16x32_bf16 v[88:91], v[200:203], v[134:137], v[88:91]
	s_cmp_eq_u32 s35, 0xa000
	s_cselect_b32 s38, s37, s36
	v_mfma_f32_16x16x32_bf16 v[84:87], v[204:207], v[134:137], v[84:87]
	v_add_u32_e32 v170, s38, v170
	v_add_u32_e32 v172, s38, v172
	s_add_u32 s35, s35, s38
	v_mfma_f32_16x16x32_bf16 v[80:83], v[208:211], v[134:137], v[80:83]
	ds_read_b128 v[212:215], v170
	v_mfma_f32_16x16x32_bf16 v[76:79], v[166:169], v[138:141], v[76:79]
	ds_read_b128 v[216:219], v170 offset:1024
	v_mfma_f32_16x16x32_bf16 v[72:75], v[200:203], v[138:141], v[72:75]
	ds_read_b128 v[220:223], v170 offset:2048
	v_mfma_f32_16x16x32_bf16 v[68:71], v[204:207], v[138:141], v[68:71]
	ds_read_b128 v[224:227], v170 offset:3072
	v_mfma_f32_16x16x32_bf16 v[64:67], v[208:211], v[138:141], v[64:67]
	ds_read_b128 v[228:231], v170 offset:4096
	v_mfma_f32_16x16x32_bf16 v[60:63], v[166:169], v[150:153], v[60:63]
	ds_read_b128 v[232:235], v170 offset:5120
	v_mfma_f32_16x16x32_bf16 v[56:59], v[200:203], v[150:153], v[56:59]
	ds_read_b128 v[244:247], v172 offset:12288
	v_mfma_f32_16x16x32_bf16 v[52:55], v[204:207], v[150:153], v[52:55]
	ds_read_b128 v[248:251], v172 offset:13312
	v_mfma_f32_16x16x32_bf16 v[48:51], v[208:211], v[150:153], v[48:51]
	ds_read_b128 v[252:255], v172 offset:14336
	v_mfma_f32_16x16x32_bf16 v[44:47], v[166:169], v[154:157], v[44:47]
	ds_read_b128 v[116:119], v172 offset:15360
	v_mfma_f32_16x16x32_bf16 v[40:43], v[200:203], v[154:157], v[40:43]
	v_mfma_f32_16x16x32_bf16 v[36:39], v[204:207], v[154:157], v[36:39]
	v_mfma_f32_16x16x32_bf16 v[32:35], v[208:211], v[154:157], v[32:35]
	v_mfma_f32_16x16x32_bf16 v[28:31], v[166:169], v[158:161], v[28:31]
	v_mfma_f32_16x16x32_bf16 v[24:27], v[200:203], v[158:161], v[24:27]
	v_mfma_f32_16x16x32_bf16 v[20:23], v[204:207], v[158:161], v[20:23]
	v_mfma_f32_16x16x32_bf16 v[16:19], v[208:211], v[158:161], v[16:19]
	v_mfma_f32_16x16x32_bf16 v[8:11], v[166:169], v[162:165], v[8:11]
	v_mfma_f32_16x16x32_bf16 v[4:7], v[200:203], v[162:165], v[4:7]
	v_mfma_f32_16x16x32_bf16 v[12:15], v[204:207], v[162:165], v[12:15]
	v_mfma_f32_16x16x32_bf16 v[0:3], v[208:211], v[162:165], v[0:3]
	s_waitcnt lgkmcnt(0)
	v_mfma_f32_16x16x32_bf16 v[92:95], v[244:247], v[212:215], v[92:95]
	v_mfma_f32_16x16x32_bf16 v[88:91], v[248:251], v[212:215], v[88:91]
	v_mfma_f32_16x16x32_bf16 v[84:87], v[252:255], v[212:215], v[84:87]
	v_mfma_f32_16x16x32_bf16 v[80:83], v[116:119], v[212:215], v[80:83]
	v_mfma_f32_16x16x32_bf16 v[76:79], v[244:247], v[216:219], v[76:79]
	v_mfma_f32_16x16x32_bf16 v[72:75], v[248:251], v[216:219], v[72:75]
	v_mfma_f32_16x16x32_bf16 v[68:71], v[252:255], v[216:219], v[68:71]
	v_mfma_f32_16x16x32_bf16 v[64:67], v[116:119], v[216:219], v[64:67]
	v_mfma_f32_16x16x32_bf16 v[60:63], v[244:247], v[220:223], v[60:63]
	v_mfma_f32_16x16x32_bf16 v[56:59], v[248:251], v[220:223], v[56:59]
	v_mfma_f32_16x16x32_bf16 v[52:55], v[252:255], v[220:223], v[52:55]
	v_mfma_f32_16x16x32_bf16 v[48:51], v[116:119], v[220:223], v[48:51]
	v_mfma_f32_16x16x32_bf16 v[44:47], v[244:247], v[224:227], v[44:47]
	v_mfma_f32_16x16x32_bf16 v[40:43], v[248:251], v[224:227], v[40:43]
	v_mfma_f32_16x16x32_bf16 v[36:39], v[252:255], v[224:227], v[36:39]
	v_mfma_f32_16x16x32_bf16 v[32:35], v[116:119], v[224:227], v[32:35]
	v_mfma_f32_16x16x32_bf16 v[28:31], v[244:247], v[228:231], v[28:31]
	v_mfma_f32_16x16x32_bf16 v[24:27], v[248:251], v[228:231], v[24:27]
	v_mfma_f32_16x16x32_bf16 v[20:23], v[252:255], v[228:231], v[20:23]
	v_mfma_f32_16x16x32_bf16 v[16:19], v[116:119], v[228:231], v[16:19]
	v_mfma_f32_16x16x32_bf16 v[8:11], v[244:247], v[232:235], v[8:11]
	v_mfma_f32_16x16x32_bf16 v[4:7], v[248:251], v[232:235], v[4:7]
	v_mfma_f32_16x16x32_bf16 v[12:15], v[252:255], v[232:235], v[12:15]
	v_mfma_f32_16x16x32_bf16 v[0:3], v[116:119], v[232:235], v[0:3]
	s_mulk_i32 s7, 0xc0
	s_add_i32 s5, s5, s51
	v_readlane_b32 s10, v242, 27
	v_readlane_b32 s11, v242, 28
	v_readlane_b32 s12, v242, 29
	v_readlane_b32 s13, v242, 30
	v_readlane_b32 s14, v243, 11
	v_readlane_b32 s15, v243, 12
	s_mov_b32 s8, 0x3fd744fd
	v_add_u32_e32 v236, s7, v145
	v_or_b32_e32 v254, s6, v146
	v_mov_b32_e32 v255, 0
	v_or_b32_e32 v237, v236, v133
	v_lshlrev_b64 v[254:255], 2, v[254:255]
	s_nop 0
	v_lshl_add_u64 v[248:249], s[10:11], 0, v[254:255]
	v_lshl_add_u64 v[250:251], s[12:13], 0, v[254:255]
	v_lshl_add_u64 v[252:253], s[14:15], 0, v[254:255]
	s_mov_b64 s[10:11], 0x5000
	v_mov_b32_e32 v255, 0
	v_lshl_add_u64 v[252:253], v[252:253], 0, s[10:11]
	v_add_u32_e32 v254, 0, v237
	v_add_u32_e32 v236, 0xfffff000, v254
	v_cmp_lt_i32_e32 vcc, 0xfff, v254
	v_lshrrev_b32_e32 v236, 10, v236
	v_lshlrev_b32_e32 v254, 12, v254
	v_add_u32_e32 v236, 1, v236
	v_cndmask_b32_e32 v236, 0, v236, vcc
	v_lshl_add_u64 v[224:225], v[254:255], 0, v[248:249]
	v_lshl_add_u64 v[228:229], v[254:255], 0, v[250:251]
	v_add_u32_e32 v236, s4, v236
	v_mad_i64_i32 v[232:233], s[0:1], v236, s33, v[252:253]
	v_add_u32_e32 v254, 16, v237
	v_add_u32_e32 v236, 0xfffff000, v254
	v_cmp_lt_i32_e32 vcc, 0xfff, v254
	v_lshrrev_b32_e32 v236, 10, v236
	v_lshlrev_b32_e32 v254, 12, v254
	v_add_u32_e32 v236, 1, v236
	v_cndmask_b32_e32 v236, 0, v236, vcc
	v_lshl_add_u64 v[226:227], v[254:255], 0, v[248:249]
	v_lshl_add_u64 v[230:231], v[254:255], 0, v[250:251]
	v_add_u32_e32 v236, s4, v236
	v_mad_i64_i32 v[234:235], s[0:1], v236, s33, v[252:253]
	global_load_dwordx4 v[154:157], v[224:225], off
	global_load_dwordx4 v[116:119], v[232:233], off
	global_load_dwordx4 v[158:161], v[224:225], off offset:64
	global_load_dwordx4 v[120:123], v[232:233], off offset:64
	global_load_dwordx4 v[162:165], v[224:225], off offset:128
	global_load_dwordx4 v[124:127], v[232:233], off offset:128
	global_load_dwordx4 v[166:169], v[224:225], off offset:192
	global_load_dwordx4 v[134:137], v[232:233], off offset:192
	global_load_dwordx4 v[208:211], v[226:227], off
	global_load_dwordx4 v[138:141], v[234:235], off
	global_load_dwordx4 v[212:215], v[226:227], off offset:64
	global_load_dwordx4 v[200:203], v[234:235], off offset:64
	global_load_dwordx4 v[216:219], v[226:227], off offset:128
	global_load_dwordx4 v[204:207], v[234:235], off offset:128
	global_load_dwordx4 v[220:223], v[226:227], off offset:192
	global_load_dwordx4 v[244:247], v[234:235], off offset:192
	s_waitcnt vmcnt(0)
	v_pk_mul_f32 v[92:93], v[92:93], v[116:117]
	v_pk_mul_f32 v[94:95], v[94:95], v[118:119]
	v_pk_fma_f32 v[92:93], v[154:155], s[8:9], v[92:93] op_sel_hi:[1,0,1]
	v_pk_fma_f32 v[94:95], v[156:157], s[8:9], v[94:95] op_sel_hi:[1,0,1]
	global_store_dwordx4 v[228:229], v[92:95], off
	v_pk_mul_f32 v[88:89], v[88:89], v[120:121]
	v_pk_mul_f32 v[90:91], v[90:91], v[122:123]
	v_pk_fma_f32 v[88:89], v[158:159], s[8:9], v[88:89] op_sel_hi:[1,0,1]
	v_pk_fma_f32 v[90:91], v[160:161], s[8:9], v[90:91] op_sel_hi:[1,0,1]
	global_store_dwordx4 v[228:229], v[88:91], off offset:64
	v_pk_mul_f32 v[84:85], v[84:85], v[124:125]
	v_pk_mul_f32 v[86:87], v[86:87], v[126:127]
	v_pk_fma_f32 v[84:85], v[162:163], s[8:9], v[84:85] op_sel_hi:[1,0,1]
	v_pk_fma_f32 v[86:87], v[164:165], s[8:9], v[86:87] op_sel_hi:[1,0,1]
	global_store_dwordx4 v[228:229], v[84:87], off offset:128
	v_pk_mul_f32 v[80:81], v[80:81], v[134:135]
	v_pk_mul_f32 v[82:83], v[82:83], v[136:137]
	v_pk_fma_f32 v[80:81], v[166:167], s[8:9], v[80:81] op_sel_hi:[1,0,1]
	v_pk_fma_f32 v[82:83], v[168:169], s[8:9], v[82:83] op_sel_hi:[1,0,1]
	global_store_dwordx4 v[228:229], v[80:83], off offset:192
	v_pk_mul_f32 v[76:77], v[76:77], v[138:139]
	v_pk_mul_f32 v[78:79], v[78:79], v[140:141]
	v_pk_fma_f32 v[76:77], v[208:209], s[8:9], v[76:77] op_sel_hi:[1,0,1]
	v_pk_fma_f32 v[78:79], v[210:211], s[8:9], v[78:79] op_sel_hi:[1,0,1]
	global_store_dwordx4 v[230:231], v[76:79], off
	v_pk_mul_f32 v[72:73], v[72:73], v[200:201]
	v_pk_mul_f32 v[74:75], v[74:75], v[202:203]
	v_pk_fma_f32 v[72:73], v[212:213], s[8:9], v[72:73] op_sel_hi:[1,0,1]
	v_pk_fma_f32 v[74:75], v[214:215], s[8:9], v[74:75] op_sel_hi:[1,0,1]
	global_store_dwordx4 v[230:231], v[72:75], off offset:64
	v_pk_mul_f32 v[68:69], v[68:69], v[204:205]
	v_pk_mul_f32 v[70:71], v[70:71], v[206:207]
	v_pk_fma_f32 v[68:69], v[216:217], s[8:9], v[68:69] op_sel_hi:[1,0,1]
	v_pk_fma_f32 v[70:71], v[218:219], s[8:9], v[70:71] op_sel_hi:[1,0,1]
	global_store_dwordx4 v[230:231], v[68:71], off offset:128
	v_pk_mul_f32 v[64:65], v[64:65], v[244:245]
	v_pk_mul_f32 v[66:67], v[66:67], v[246:247]
	v_pk_fma_f32 v[64:65], v[220:221], s[8:9], v[64:65] op_sel_hi:[1,0,1]
	v_pk_fma_f32 v[66:67], v[222:223], s[8:9], v[66:67] op_sel_hi:[1,0,1]
	global_store_dwordx4 v[230:231], v[64:67], off offset:192
	v_add_u32_e32 v254, 32, v237
	v_add_u32_e32 v236, 0xfffff000, v254
	v_cmp_lt_i32_e32 vcc, 0xfff, v254
	v_lshrrev_b32_e32 v236, 10, v236
	v_lshlrev_b32_e32 v254, 12, v254
	v_add_u32_e32 v236, 1, v236
	v_cndmask_b32_e32 v236, 0, v236, vcc
	v_lshl_add_u64 v[224:225], v[254:255], 0, v[248:249]
	v_lshl_add_u64 v[228:229], v[254:255], 0, v[250:251]
	v_add_u32_e32 v236, s4, v236
	v_mad_i64_i32 v[232:233], s[0:1], v236, s33, v[252:253]
	v_add_u32_e32 v254, 48, v237
	v_add_u32_e32 v236, 0xfffff000, v254
	v_cmp_lt_i32_e32 vcc, 0xfff, v254
	v_lshrrev_b32_e32 v236, 10, v236
	v_lshlrev_b32_e32 v254, 12, v254
	v_add_u32_e32 v236, 1, v236
	v_cndmask_b32_e32 v236, 0, v236, vcc
	v_lshl_add_u64 v[226:227], v[254:255], 0, v[248:249]
	v_lshl_add_u64 v[230:231], v[254:255], 0, v[250:251]
	v_add_u32_e32 v236, s4, v236
	v_mad_i64_i32 v[234:235], s[0:1], v236, s33, v[252:253]
	global_load_dwordx4 v[154:157], v[224:225], off
	global_load_dwordx4 v[116:119], v[232:233], off
	global_load_dwordx4 v[158:161], v[224:225], off offset:64
	global_load_dwordx4 v[120:123], v[232:233], off offset:64
	global_load_dwordx4 v[162:165], v[224:225], off offset:128
	global_load_dwordx4 v[124:127], v[232:233], off offset:128
	global_load_dwordx4 v[166:169], v[224:225], off offset:192
	global_load_dwordx4 v[134:137], v[232:233], off offset:192
	global_load_dwordx4 v[208:211], v[226:227], off
	global_load_dwordx4 v[138:141], v[234:235], off
	global_load_dwordx4 v[212:215], v[226:227], off offset:64
	global_load_dwordx4 v[200:203], v[234:235], off offset:64
	global_load_dwordx4 v[216:219], v[226:227], off offset:128
	global_load_dwordx4 v[204:207], v[234:235], off offset:128
	global_load_dwordx4 v[220:223], v[226:227], off offset:192
	global_load_dwordx4 v[244:247], v[234:235], off offset:192
	s_waitcnt vmcnt(0)
	v_pk_mul_f32 v[60:61], v[60:61], v[116:117]
	v_pk_mul_f32 v[62:63], v[62:63], v[118:119]
	v_pk_fma_f32 v[60:61], v[154:155], s[8:9], v[60:61] op_sel_hi:[1,0,1]
	v_pk_fma_f32 v[62:63], v[156:157], s[8:9], v[62:63] op_sel_hi:[1,0,1]
	global_store_dwordx4 v[228:229], v[60:63], off
	v_pk_mul_f32 v[56:57], v[56:57], v[120:121]
	v_pk_mul_f32 v[58:59], v[58:59], v[122:123]
	v_pk_fma_f32 v[56:57], v[158:159], s[8:9], v[56:57] op_sel_hi:[1,0,1]
	v_pk_fma_f32 v[58:59], v[160:161], s[8:9], v[58:59] op_sel_hi:[1,0,1]
	global_store_dwordx4 v[228:229], v[56:59], off offset:64
	v_pk_mul_f32 v[52:53], v[52:53], v[124:125]
	v_pk_mul_f32 v[54:55], v[54:55], v[126:127]
	v_pk_fma_f32 v[52:53], v[162:163], s[8:9], v[52:53] op_sel_hi:[1,0,1]
	v_pk_fma_f32 v[54:55], v[164:165], s[8:9], v[54:55] op_sel_hi:[1,0,1]
	global_store_dwordx4 v[228:229], v[52:55], off offset:128
	v_pk_mul_f32 v[48:49], v[48:49], v[134:135]
	v_pk_mul_f32 v[50:51], v[50:51], v[136:137]
	v_pk_fma_f32 v[48:49], v[166:167], s[8:9], v[48:49] op_sel_hi:[1,0,1]
	v_pk_fma_f32 v[50:51], v[168:169], s[8:9], v[50:51] op_sel_hi:[1,0,1]
	global_store_dwordx4 v[228:229], v[48:51], off offset:192
	v_pk_mul_f32 v[44:45], v[44:45], v[138:139]
	v_pk_mul_f32 v[46:47], v[46:47], v[140:141]
	v_pk_fma_f32 v[44:45], v[208:209], s[8:9], v[44:45] op_sel_hi:[1,0,1]
	v_pk_fma_f32 v[46:47], v[210:211], s[8:9], v[46:47] op_sel_hi:[1,0,1]
	global_store_dwordx4 v[230:231], v[44:47], off
	v_pk_mul_f32 v[40:41], v[40:41], v[200:201]
	v_pk_mul_f32 v[42:43], v[42:43], v[202:203]
	v_pk_fma_f32 v[40:41], v[212:213], s[8:9], v[40:41] op_sel_hi:[1,0,1]
	v_pk_fma_f32 v[42:43], v[214:215], s[8:9], v[42:43] op_sel_hi:[1,0,1]
	global_store_dwordx4 v[230:231], v[40:43], off offset:64
	v_pk_mul_f32 v[36:37], v[36:37], v[204:205]
	v_pk_mul_f32 v[38:39], v[38:39], v[206:207]
	v_pk_fma_f32 v[36:37], v[216:217], s[8:9], v[36:37] op_sel_hi:[1,0,1]
	v_pk_fma_f32 v[38:39], v[218:219], s[8:9], v[38:39] op_sel_hi:[1,0,1]
	global_store_dwordx4 v[230:231], v[36:39], off offset:128
	v_pk_mul_f32 v[32:33], v[32:33], v[244:245]
	v_pk_mul_f32 v[34:35], v[34:35], v[246:247]
	v_pk_fma_f32 v[32:33], v[220:221], s[8:9], v[32:33] op_sel_hi:[1,0,1]
	v_pk_fma_f32 v[34:35], v[222:223], s[8:9], v[34:35] op_sel_hi:[1,0,1]
	global_store_dwordx4 v[230:231], v[32:35], off offset:192
	v_add_u32_e32 v254, 64, v237
	v_add_u32_e32 v236, 0xfffff000, v254
	v_cmp_lt_i32_e32 vcc, 0xfff, v254
	v_lshrrev_b32_e32 v236, 10, v236
	v_lshlrev_b32_e32 v254, 12, v254
	v_add_u32_e32 v236, 1, v236
	v_cndmask_b32_e32 v236, 0, v236, vcc
	v_lshl_add_u64 v[224:225], v[254:255], 0, v[248:249]
	v_lshl_add_u64 v[228:229], v[254:255], 0, v[250:251]
	v_add_u32_e32 v236, s4, v236
	v_mad_i64_i32 v[232:233], s[0:1], v236, s33, v[252:253]
	v_add_u32_e32 v254, 80, v237
	v_add_u32_e32 v236, 0xfffff000, v254
	v_cmp_lt_i32_e32 vcc, 0xfff, v254
	v_lshrrev_b32_e32 v236, 10, v236
	v_lshlrev_b32_e32 v254, 12, v254
	v_add_u32_e32 v236, 1, v236
	v_cndmask_b32_e32 v236, 0, v236, vcc
	v_lshl_add_u64 v[226:227], v[254:255], 0, v[248:249]
	v_lshl_add_u64 v[230:231], v[254:255], 0, v[250:251]
	v_add_u32_e32 v236, s4, v236
	v_mad_i64_i32 v[234:235], s[0:1], v236, s33, v[252:253]
	global_load_dwordx4 v[154:157], v[224:225], off
	global_load_dwordx4 v[116:119], v[232:233], off
	global_load_dwordx4 v[158:161], v[224:225], off offset:64
	global_load_dwordx4 v[120:123], v[232:233], off offset:64
	global_load_dwordx4 v[162:165], v[224:225], off offset:128
	global_load_dwordx4 v[124:127], v[232:233], off offset:128
	global_load_dwordx4 v[166:169], v[224:225], off offset:192
	global_load_dwordx4 v[134:137], v[232:233], off offset:192
	global_load_dwordx4 v[208:211], v[226:227], off
	global_load_dwordx4 v[138:141], v[234:235], off
	global_load_dwordx4 v[212:215], v[226:227], off offset:64
	global_load_dwordx4 v[200:203], v[234:235], off offset:64
	global_load_dwordx4 v[216:219], v[226:227], off offset:128
	global_load_dwordx4 v[204:207], v[234:235], off offset:128
	global_load_dwordx4 v[220:223], v[226:227], off offset:192
	global_load_dwordx4 v[244:247], v[234:235], off offset:192
	s_waitcnt vmcnt(0)
	v_pk_mul_f32 v[28:29], v[28:29], v[116:117]
	v_pk_mul_f32 v[30:31], v[30:31], v[118:119]
	v_pk_fma_f32 v[28:29], v[154:155], s[8:9], v[28:29] op_sel_hi:[1,0,1]
	v_pk_fma_f32 v[30:31], v[156:157], s[8:9], v[30:31] op_sel_hi:[1,0,1]
	global_store_dwordx4 v[228:229], v[28:31], off
	v_pk_mul_f32 v[24:25], v[24:25], v[120:121]
	v_pk_mul_f32 v[26:27], v[26:27], v[122:123]
	v_pk_fma_f32 v[24:25], v[158:159], s[8:9], v[24:25] op_sel_hi:[1,0,1]
	v_pk_fma_f32 v[26:27], v[160:161], s[8:9], v[26:27] op_sel_hi:[1,0,1]
	global_store_dwordx4 v[228:229], v[24:27], off offset:64
	v_pk_mul_f32 v[20:21], v[20:21], v[124:125]
	v_pk_mul_f32 v[22:23], v[22:23], v[126:127]
	v_pk_fma_f32 v[20:21], v[162:163], s[8:9], v[20:21] op_sel_hi:[1,0,1]
	v_pk_fma_f32 v[22:23], v[164:165], s[8:9], v[22:23] op_sel_hi:[1,0,1]
	global_store_dwordx4 v[228:229], v[20:23], off offset:128
	v_pk_mul_f32 v[16:17], v[16:17], v[134:135]
	v_pk_mul_f32 v[18:19], v[18:19], v[136:137]
	v_pk_fma_f32 v[16:17], v[166:167], s[8:9], v[16:17] op_sel_hi:[1,0,1]
	v_pk_fma_f32 v[18:19], v[168:169], s[8:9], v[18:19] op_sel_hi:[1,0,1]
	global_store_dwordx4 v[228:229], v[16:19], off offset:192
	v_pk_mul_f32 v[8:9], v[8:9], v[138:139]
	v_pk_mul_f32 v[10:11], v[10:11], v[140:141]
	v_pk_fma_f32 v[8:9], v[208:209], s[8:9], v[8:9] op_sel_hi:[1,0,1]
	v_pk_fma_f32 v[10:11], v[210:211], s[8:9], v[10:11] op_sel_hi:[1,0,1]
	global_store_dwordx4 v[230:231], v[8:11], off
	v_pk_mul_f32 v[4:5], v[4:5], v[200:201]
	v_pk_mul_f32 v[6:7], v[6:7], v[202:203]
	v_pk_fma_f32 v[4:5], v[212:213], s[8:9], v[4:5] op_sel_hi:[1,0,1]
	v_pk_fma_f32 v[6:7], v[214:215], s[8:9], v[6:7] op_sel_hi:[1,0,1]
	global_store_dwordx4 v[230:231], v[4:7], off offset:64
	v_pk_mul_f32 v[12:13], v[12:13], v[204:205]
	v_pk_mul_f32 v[14:15], v[14:15], v[206:207]
	v_pk_fma_f32 v[12:13], v[216:217], s[8:9], v[12:13] op_sel_hi:[1,0,1]
	v_pk_fma_f32 v[14:15], v[218:219], s[8:9], v[14:15] op_sel_hi:[1,0,1]
	global_store_dwordx4 v[230:231], v[12:15], off offset:128
	v_pk_mul_f32 v[0:1], v[0:1], v[244:245]
	v_pk_mul_f32 v[2:3], v[2:3], v[246:247]
	v_pk_fma_f32 v[0:1], v[220:221], s[8:9], v[0:1] op_sel_hi:[1,0,1]
	v_pk_fma_f32 v[2:3], v[222:223], s[8:9], v[2:3] op_sel_hi:[1,0,1]
	global_store_dwordx4 v[230:231], v[0:3], off offset:192
	v_readlane_b32 s9, v242, 26
	v_readlane_b32 s10, v242, 27
	v_readlane_b32 s11, v242, 28
	v_readlane_b32 s12, v242, 29
	v_readlane_b32 s13, v242, 30
	v_readlane_b32 s14, v242, 31
	v_readlane_b32 s15, v242, 32
	v_readlane_b32 s16, v242, 33
	v_readlane_b32 s17, v242, 34
	v_readlane_b32 s18, v242, 35
	v_readlane_b32 s19, v242, 36
	v_readlane_b32 s20, v242, 37
	v_readlane_b32 s21, v242, 38
	v_readlane_b32 s22, v242, 39
	v_readlane_b32 s23, v242, 40
	s_mov_b64 s[24:25], 0x5000
	s_movk_i32 s6, 0xfff
	s_waitcnt lgkmcnt(0)
	s_barrier
	s_cmpk_gt_i32 s5, 0xff
	s_cbranch_scc0 .LBB0_52
